# retention waves 4-7 inner block: second LDS read group issued before the first MFMA pair into separate registers (on v52)
# baseline (speedup 1.0000x reference)
; #define LAS __attribute__((address_space(3)))
; __device__ __forceinline__ unsigned cvt_pk_bf16(float lo, float hi) { f32x2 v = {lo, hi}; bf16x2_t b = __builtin_convertvector(v, bf16x2_t); return __builtin_bit_cast(unsigned, b); }
; __device__ __forceinline__ void ret_mfma(const Params& P, LAS unsigned char* lds, int wave) {
;     ...
;             if (wave >= 4) {
;                 const int w4 = wave - 4, dvblk = w4 >> 1, nblk = w4 & 1, n = nblk * 32 + q32;
; #pragma unroll
;                 for (int ks = 0; ks < 4; ++ks) {
;                     const LAS unsigned char* p = lds + V_OFF + (16 * ks + trrow) * VP + dvblk * 64 + trcol;
;                     const bf16x8 a = tr_pair(p, p + 4 * VP);
;                     const bf16x8 bs = *(const LAS bf16x8*)(lds + S_OFF + n * SP + (16 * ks + 8 * hf) * 2);
;                     acc = __builtin_amdgcn_mfma_f32_32x32x16_bf16(a, bs, acc, 0, 0, 0);
;                 }
;                 float sq = 0.f;
; #pragma unroll
;                 for (int i = 0; i < 16; ++i) sq += acc[i] * acc[i];
;                 sq += __shfl_xor(sq, 32);
;                 if (hf == 0) rssq[(r0 + n) * 64 + hh * 16 + slice * 2 + dvblk] = sq;
;                 bf16_t* op = V + (r0 + n) * 2048 + hh * 512 + slice * 64 + dvblk * 32 + 4 * hf;
; #pragma unroll
;                 for (int j = 0; j < 4; ++j) { u32x2 w; w.x = cvt_pk_bf16(acc[4 * j], acc[4 * j + 1]); w.y = cvt_pk_bf16(acc[4 * j + 2], acc[4 * j + 3]); *(u32x2*)(op + 8 * j) = w; }
;             }
.Lret_w47:
	ds_read_b64_tr_b16 v[190:191], v181
	ds_read_b64_tr_b16 v[192:193], v181 offset:768
	v_add_u32_e32 v103, v151, v149
	ds_read_b128 v[194:197], v103
	ds_read_b64_tr_b16 v[198:199], v181 offset:3072
	ds_read_b64_tr_b16 v[200:201], v181 offset:3840
	ds_read_b128 v[202:205], v103 offset:32
	v_cvt_pk_bf16_f32 v218, v0, v1
	v_cvt_pk_bf16_f32 v219, v2, v3
	ds_write_b64 v242, v[218:219]
	v_cvt_pk_bf16_f32 v220, v4, v5
	v_cvt_pk_bf16_f32 v221, v6, v7
	ds_write_b64 v242, v[220:221] offset:16
	v_cvt_pk_bf16_f32 v222, v8, v9
	v_cvt_pk_bf16_f32 v223, v10, v11
	ds_write_b64 v242, v[222:223] offset:32
	v_cvt_pk_bf16_f32 v224, v12, v13
	v_cvt_pk_bf16_f32 v225, v14, v15
	ds_write_b64 v242, v[224:225] offset:48
	v_cvt_pk_bf16_f32 v218, v16, v17
	v_cvt_pk_bf16_f32 v219, v18, v19
	ds_write_b64 v242, v[218:219] offset:16896
	v_cvt_pk_bf16_f32 v220, v20, v21
	v_cvt_pk_bf16_f32 v221, v22, v23
	ds_write_b64 v242, v[220:221] offset:16912
	v_cvt_pk_bf16_f32 v222, v24, v25
	v_cvt_pk_bf16_f32 v223, v26, v27
	ds_write_b64 v242, v[222:223] offset:16928
	v_cvt_pk_bf16_f32 v224, v28, v29
	v_cvt_pk_bf16_f32 v225, v30, v31
	ds_write_b64 v242, v[224:225] offset:16944
	ds_read_b64_tr_b16 v[210:211], v181 offset:6144
	ds_read_b64_tr_b16 v[212:213], v181 offset:6912
	ds_read_b128 v[218:221], v103 offset:64
	ds_read_b64_tr_b16 v[214:215], v181 offset:9216
	ds_read_b64_tr_b16 v[216:217], v181 offset:9984
	ds_read_b128 v[222:225], v103 offset:96
	s_waitcnt lgkmcnt(6)
	v_mfma_f32_32x32x16_bf16 v[32:47], v[190:193], v[194:197], v[32:47]
	s_lshl_b32 s8, s29, 6
	s_or_b32 s8, s18, s8
	v_or_b32_e32 v146, s8, v84
	v_mfma_f32_32x32x16_bf16 v[32:47], v[198:201], v[202:205], v[32:47]
	s_waitcnt lgkmcnt(0)
	v_mfma_f32_32x32x16_bf16 v[32:47], v[210:213], v[218:221], v[32:47]
	v_mfma_f32_32x32x16_bf16 v[32:47], v[214:217], v[222:225], v[32:47]
	v_mov_b32_e32 v147, s19
	v_lshlrev_b64 v[190:191], 8, v[146:147]
	v_lshlrev_b64 v[146:147], 12, v[146:147]
	v_lshl_add_u64 v[190:191], s[20:21], 0, v[190:191]
	v_lshl_add_u64 v[146:147], v[128:129], 0, v[146:147]
	v_lshl_add_u64 v[146:147], v[146:147], 0, v[142:143]
	s_nop 5
	v_pk_mul_f32 v[192:193], v[32:33], v[32:33]
	v_pk_mul_f32 v[194:195], v[34:35], v[34:35]
	v_pk_fma_f32 v[192:193], v[36:37], v[36:37], v[192:193]
	v_pk_fma_f32 v[194:195], v[38:39], v[38:39], v[194:195]
	v_pk_fma_f32 v[192:193], v[40:41], v[40:41], v[192:193]
	v_pk_fma_f32 v[194:195], v[42:43], v[42:43], v[194:195]
	v_pk_fma_f32 v[192:193], v[44:45], v[44:45], v[192:193]
	v_pk_fma_f32 v[194:195], v[46:47], v[46:47], v[194:195]
	v_pk_add_f32 v[192:193], v[192:193], v[194:195]
	v_cvt_pk_bf16_f32 v32, v32, v33
	v_cvt_pk_bf16_f32 v33, v34, v35
	v_add_f32_e32 v103, v192, v193
	v_cvt_pk_bf16_f32 v34, v36, v37
	v_mov_b32_e32 v107, v103
	v_cvt_pk_bf16_f32 v35, v38, v39
	v_cvt_pk_bf16_f32 v36, v40, v41
	v_permlane32_swap_b32_e32 v103, v107
	v_cvt_pk_bf16_f32 v37, v42, v43
	v_cvt_pk_bf16_f32 v38, v44, v45
	v_cvt_pk_bf16_f32 v39, v46, v47
	v_add_f32_e32 v103, v103, v107
	v_permlane32_swap_b32_e32 v32, v34
	v_permlane32_swap_b32_e32 v33, v35
	v_permlane32_swap_b32_e32 v36, v38
	v_permlane32_swap_b32_e32 v37, v39
	global_store_dwordx4 v[146:147], v[32:35], off
	global_store_dwordx4 v[146:147], v[36:39], off offset:32
	s_mov_b64 s[8:9], exec
	s_andn2_b64 exec, exec, s[6:7]
	global_store_dword v[190:191], v103, off
	s_mov_b64 exec, s[8:9]
	s_branch .LBB0_254
